# MLA: running-max overflow check on every other key tile (tile 0 included); deferred rescale otherwise unchanged
# baseline (speedup 1.0000x reference)
.Lmla_nowrite_A:
	s_waitcnt lgkmcnt(9)
	v_mfma_f32_32x32x16_bf16 v[64:79], v[178:181], v[100:103], v[64:79]
	s_waitcnt lgkmcnt(8)
	v_mfma_f32_32x32x16_bf16 v[48:63], v[198:201], v[100:103], v[48:63]
	s_setprio 0
	s_nop 10
	s_bitcmp1_b32 s28, 0
	s_cbranch_scc1 .Lmla_norescale_A
	v_max_f32_e32 v172, v64, v65
	v_max3_f32 v173, v66, v67, v49
	v_max3_f32 v172, v172, v48, v50
	v_max3_f32 v172, v172, v51, v68
	v_max3_f32 v173, v173, v70, v71
	s_nop 1
	v_max3_f32 v172, v172, v69, v52
	v_max3_f32 v173, v173, v54, v55
	v_max3_f32 v172, v172, v53, v72
	v_max3_f32 v173, v173, v74, v75
	v_max3_f32 v172, v172, v73, v56
	s_nop 1
	v_max3_f32 v173, v173, v58, v59
	v_max3_f32 v172, v172, v57, v76
	v_max3_f32 v173, v173, v78, v79
	v_max3_f32 v172, v172, v77, v60
	v_max3_f32 v173, v173, v62, v63
	s_nop 1
	v_max3_f32 v172, v172, v61, v173
	v_mov_b32_e32 v173, v172
	s_nop 1
	v_permlane32_swap_b32_e32 v172, v173
	v_max_f32_e32 v177, v172, v173
	v_cmp_lt_f32_e32 vcc, s14, v177
	s_nop 1
	s_cbranch_vccz .Lmla_norescale_A
	v_max_f32_e32 v172, s15, v177
	v_max_f32_e32 v173, 0xc2c80000, v172
	v_exp_f32_e64 v173, -v173
	v_add_f32_e32 v156, v156, v172
	s_nop 1
	v_sub_f32_e32 v48, v48, v172
	v_sub_f32_e32 v49, v49, v172
	v_sub_f32_e32 v50, v50, v172
	v_sub_f32_e32 v51, v51, v172
	v_sub_f32_e32 v52, v52, v172
	s_nop 1
	v_sub_f32_e32 v53, v53, v172
	v_sub_f32_e32 v54, v54, v172
	v_sub_f32_e32 v55, v55, v172
	v_sub_f32_e32 v56, v56, v172
	v_sub_f32_e32 v57, v57, v172
	s_nop 1
	v_sub_f32_e32 v58, v58, v172
	v_sub_f32_e32 v59, v59, v172
	v_sub_f32_e32 v60, v60, v172
	v_sub_f32_e32 v61, v61, v172
	v_sub_f32_e32 v62, v62, v172
	s_nop 1
	v_sub_f32_e32 v63, v63, v172
	v_sub_f32_e32 v64, v64, v172
	v_sub_f32_e32 v65, v65, v172
	v_sub_f32_e32 v66, v66, v172
	v_sub_f32_e32 v67, v67, v172
	s_nop 1
	v_sub_f32_e32 v68, v68, v172
	v_sub_f32_e32 v69, v69, v172
	v_sub_f32_e32 v70, v70, v172
	v_sub_f32_e32 v71, v71, v172
	v_sub_f32_e32 v72, v72, v172
	s_nop 1
	v_sub_f32_e32 v73, v73, v172
	v_sub_f32_e32 v74, v74, v172
	v_sub_f32_e32 v75, v75, v172
	v_sub_f32_e32 v76, v76, v172
	v_sub_f32_e32 v77, v77, v172
	s_nop 1
	v_sub_f32_e32 v78, v78, v172
	v_sub_f32_e32 v79, v79, v172
	v_mul_f32_e32 v0, v0, v173
	v_mul_f32_e32 v1, v1, v173
	v_mul_f32_e32 v2, v2, v173
	s_nop 1
	v_mul_f32_e32 v3, v3, v173
	v_mul_f32_e32 v4, v4, v173
	v_mul_f32_e32 v5, v5, v173
	v_mul_f32_e32 v6, v6, v173
	v_mul_f32_e32 v7, v7, v173
	s_nop 1
	v_mul_f32_e32 v8, v8, v173
	v_mul_f32_e32 v9, v9, v173
	v_mul_f32_e32 v10, v10, v173
	v_mul_f32_e32 v11, v11, v173
	v_mul_f32_e32 v12, v12, v173
	s_nop 1
	v_mul_f32_e32 v13, v13, v173
	v_mul_f32_e32 v14, v14, v173
	v_mul_f32_e32 v15, v15, v173
	v_mul_f32_e32 v16, v16, v173
	v_mul_f32_e32 v17, v17, v173
	s_nop 1
	v_mul_f32_e32 v18, v18, v173
	v_mul_f32_e32 v19, v19, v173
	v_mul_f32_e32 v20, v20, v173
	v_mul_f32_e32 v21, v21, v173
	v_mul_f32_e32 v22, v22, v173
	s_nop 1
	v_mul_f32_e32 v23, v23, v173
	v_mul_f32_e32 v24, v24, v173
	v_mul_f32_e32 v25, v25, v173
	v_mul_f32_e32 v26, v26, v173
	v_mul_f32_e32 v27, v27, v173
	s_nop 1
	v_mul_f32_e32 v28, v28, v173
	v_mul_f32_e32 v29, v29, v173
	v_mul_f32_e32 v30, v30, v173
	v_mul_f32_e32 v31, v31, v173
	v_mul_f32_e32 v157, v157, v173
	s_nop 1
	v_sub_f32_e32 v32, 0, v156
	v_mov_b32_e32 v33, v32
	v_mov_b32_e32 v34, v32
	v_mov_b32_e32 v35, v32
	v_mov_b32_e32 v36, v32
	s_nop 1
	v_mov_b32_e32 v37, v32
	v_mov_b32_e32 v38, v32
	v_mov_b32_e32 v39, v32
	v_mov_b32_e32 v40, v32
	v_mov_b32_e32 v41, v32
	s_nop 1
	v_mov_b32_e32 v42, v32
	v_mov_b32_e32 v43, v32
	v_mov_b32_e32 v44, v32
	v_mov_b32_e32 v45, v32
	v_mov_b32_e32 v46, v32
	s_nop 1
	v_mov_b32_e32 v47, v32

.Lmla_B_loop:
	s_bitcmp1_b32 s28, 0
	s_cbranch_scc0 .Lmla_norescale_B
	v_max_f32_e32 v172, v64, v65
	v_max3_f32 v173, v66, v67, v49
	v_max3_f32 v172, v172, v48, v50
	v_max3_f32 v172, v172, v51, v68
	v_max3_f32 v173, v173, v70, v71
	v_max3_f32 v172, v172, v69, v52
	v_max3_f32 v173, v173, v54, v55
	v_max3_f32 v172, v172, v53, v72
	v_max3_f32 v173, v173, v74, v75
	v_max3_f32 v172, v172, v73, v56
	v_max3_f32 v173, v173, v58, v59
	v_max3_f32 v172, v172, v57, v76
	v_max3_f32 v173, v173, v78, v79
	v_max3_f32 v172, v172, v77, v60
	v_max3_f32 v173, v173, v62, v63
	v_max3_f32 v172, v172, v61, v173
	v_mov_b32_e32 v173, v172
	s_nop 1
	v_permlane32_swap_b32_e32 v172, v173
	v_max_f32_e32 v177, v172, v173
	v_cmp_lt_f32_e32 vcc, s14, v177
	s_cbranch_vccz .Lmla_norescale_B
	v_max_f32_e32 v172, s15, v177
	v_max_f32_e32 v173, 0xc2c80000, v172
	v_exp_f32_e64 v173, -v173
	v_add_f32_e32 v156, v156, v172
	v_sub_f32_e32 v48, v48, v172
	v_sub_f32_e32 v49, v49, v172
	v_sub_f32_e32 v50, v50, v172
	v_sub_f32_e32 v51, v51, v172
	v_sub_f32_e32 v52, v52, v172
	v_sub_f32_e32 v53, v53, v172
	v_sub_f32_e32 v54, v54, v172
	v_sub_f32_e32 v55, v55, v172
	v_sub_f32_e32 v56, v56, v172
	v_sub_f32_e32 v57, v57, v172
	v_sub_f32_e32 v58, v58, v172
	v_sub_f32_e32 v59, v59, v172
	v_sub_f32_e32 v60, v60, v172
	v_sub_f32_e32 v61, v61, v172
	v_sub_f32_e32 v62, v62, v172
	v_sub_f32_e32 v63, v63, v172
	v_sub_f32_e32 v64, v64, v172
	v_sub_f32_e32 v65, v65, v172
	v_sub_f32_e32 v66, v66, v172
	v_sub_f32_e32 v67, v67, v172
	v_sub_f32_e32 v68, v68, v172
	v_sub_f32_e32 v69, v69, v172
	v_sub_f32_e32 v70, v70, v172
	v_sub_f32_e32 v71, v71, v172
	v_sub_f32_e32 v72, v72, v172
	v_sub_f32_e32 v73, v73, v172
	v_sub_f32_e32 v74, v74, v172
	v_sub_f32_e32 v75, v75, v172
	v_sub_f32_e32 v76, v76, v172
	v_sub_f32_e32 v77, v77, v172
	v_sub_f32_e32 v78, v78, v172
	v_sub_f32_e32 v79, v79, v172
	v_mul_f32_e32 v0, v0, v173
	v_mul_f32_e32 v1, v1, v173
	v_mul_f32_e32 v2, v2, v173
	v_mul_f32_e32 v3, v3, v173
	v_mul_f32_e32 v4, v4, v173
	v_mul_f32_e32 v5, v5, v173
	v_mul_f32_e32 v6, v6, v173
	v_mul_f32_e32 v7, v7, v173
	v_mul_f32_e32 v8, v8, v173
	v_mul_f32_e32 v9, v9, v173
	v_mul_f32_e32 v10, v10, v173
	v_mul_f32_e32 v11, v11, v173
	v_mul_f32_e32 v12, v12, v173
	v_mul_f32_e32 v13, v13, v173
	v_mul_f32_e32 v14, v14, v173
	v_mul_f32_e32 v15, v15, v173
	v_mul_f32_e32 v16, v16, v173
	v_mul_f32_e32 v17, v17, v173
	v_mul_f32_e32 v18, v18, v173
	v_mul_f32_e32 v19, v19, v173
	v_mul_f32_e32 v20, v20, v173
	v_mul_f32_e32 v21, v21, v173
	v_mul_f32_e32 v22, v22, v173
	v_mul_f32_e32 v23, v23, v173
	v_mul_f32_e32 v24, v24, v173
	v_mul_f32_e32 v25, v25, v173
	v_mul_f32_e32 v26, v26, v173
	v_mul_f32_e32 v27, v27, v173
	v_mul_f32_e32 v28, v28, v173
	v_mul_f32_e32 v29, v29, v173
	v_mul_f32_e32 v30, v30, v173
	v_mul_f32_e32 v31, v31, v173
	v_mul_f32_e32 v157, v157, v173
	v_sub_f32_e32 v32, 0, v156
	v_mov_b32_e32 v33, v32
	v_mov_b32_e32 v34, v32
	v_mov_b32_e32 v35, v32
	v_mov_b32_e32 v36, v32
	v_mov_b32_e32 v37, v32
	v_mov_b32_e32 v38, v32
	v_mov_b32_e32 v39, v32
	v_mov_b32_e32 v40, v32
	v_mov_b32_e32 v41, v32
	v_mov_b32_e32 v42, v32
	v_mov_b32_e32 v43, v32
	v_mov_b32_e32 v44, v32
	v_mov_b32_e32 v45, v32
	v_mov_b32_e32 v46, v32
	v_mov_b32_e32 v47, v32
